# SGU epilogue: all 32 (bias,u) loads issued up front with counted vmcnt instead of one pair per column tile behind the previous store
# baseline (speedup 1.0000x reference)
; #define LAS __attribute__((address_space(3)))
; __device__ __forceinline__ unsigned pk2(float lo, float hi) { typedef float f2_t __attribute__((ext_vector_type(2))); typedef __bf16 b2_t __attribute__((ext_vector_type(2))); const f2_t v = {lo, hi}; return __builtin_bit_cast(unsigned, __builtin_convertvector(v, b2_t)); }
; __device__ __forceinline__ void sgu_unit(LAS unsigned char* lds, const bf16* U, bf16* Uout, const bf16* Zb, const float* stats, const float* lng, const float* lnb, const bf16* wsm, const float* bs,
;                                          int unit, int tid, int wave, int lane) {
;     ...
;     for (int ks = 0; ks < nks; ++ks) {
;         bf16x8 wb[4];
; #pragma unroll
;         for (int gi = 0; gi < 4; ++gi) wb[gi] = *(const bf16x8*)(wsm + ((size_t)((gq * 4 + gi) * 128 + t)) * 128 + ks * 32 + fq * 8);
; #pragma unroll
;         for (int ct = 0; ct < 16; ++ct) {
;             const bf16x8 za = *(const LAS bf16x8*)(zt + (ct * 16 + fr) * ZT_LD + ks * 32 + fq * 8);
;             acc[ct] = __builtin_amdgcn_mfma_f32_16x16x32_bf16(za, wb[ct >> 2], acc[ct], 0, 0, 0);
;         }
;     }
;     const bf16* urow = U + (size_t)(row0 + t) * SW + colbase + fq * 4; bf16* uorow = Uout + (size_t)(row0 + t) * SW + colbase + fq * 4;
; #pragma unroll
;     for (int ct = 0; ct < 16; ++ct) {
;         const float bias = bs[(gq * 4 + (ct >> 2)) * 128 + t];
;         const v2u uw = *(const v2u*)(urow + ct * 16);
;         const float u0 = __uint_as_float(uw.x << 16), u1 = __uint_as_float(uw.x & 0xffff0000u), u2 = __uint_as_float(uw.y << 16), u3 = __uint_as_float(uw.y & 0xffff0000u);
;         v2u w; w.x = pk2(u0 * (acc[ct][0] + bias), u1 * (acc[ct][1] + bias)); w.y = pk2(u2 * (acc[ct][2] + bias), u3 * (acc[ct][3] + bias));
;         *(v2u*)(uorow + ct * 16) = w;
.LBB0_388:
	global_load_dwordx4 v[176:179], v[94:95], off
	v_add_u32_e32 v66, s6, v126
	ds_read_b128 v[180:183], v66
	ds_read_b128 v[184:187], v66 offset:4352
	v_add_u32_e32 v87, s6, v125
	v_add_u32_e32 v89, s6, v124
	v_lshl_add_u64 v[94:95], v[94:95], 0, 64
	s_waitcnt vmcnt(0) lgkmcnt(1)
	v_mfma_f32_16x16x32_bf16 v[60:63], v[180:183], v[176:179], v[60:63]
	global_load_dwordx4 v[180:183], v[96:97], off
	v_lshl_add_u64 v[96:97], v[96:97], 0, 64
	s_waitcnt lgkmcnt(0)
	v_mfma_f32_16x16x32_bf16 v[56:59], v[184:187], v[176:179], v[56:59]
	ds_read_b128 v[184:187], v66 offset:8704
	ds_read_b128 v[194:197], v66 offset:17408
	s_waitcnt lgkmcnt(1)
	v_mfma_f32_16x16x32_bf16 v[52:55], v[184:187], v[176:179], v[52:55]
	ds_read_b128 v[184:187], v87
	ds_read_b128 v[198:201], v89
	v_add_u32_e32 v87, s6, v123
	v_add_u32_e32 v89, s6, v122
	s_waitcnt lgkmcnt(1)
	v_mfma_f32_16x16x32_bf16 v[48:51], v[184:187], v[176:179], v[48:51]
	ds_read_b128 v[176:179], v66 offset:21760
	ds_read_b128 v[184:187], v66 offset:26112
	s_add_i32 s6, s6, 64
	s_cmp_lg_u32 s96, s6
	s_waitcnt vmcnt(0) lgkmcnt(1)
	v_mfma_f32_16x16x32_bf16 v[40:43], v[176:179], v[180:183], v[40:43]
	global_load_dwordx4 v[176:179], v[98:99], off
	v_lshl_add_u64 v[98:99], v[98:99], 0, 64
	v_mfma_f32_16x16x32_bf16 v[44:47], v[194:197], v[180:183], v[44:47]
	s_waitcnt lgkmcnt(0)
	v_mfma_f32_16x16x32_bf16 v[36:39], v[184:187], v[180:183], v[36:39]
	v_mfma_f32_16x16x32_bf16 v[32:35], v[198:201], v[180:183], v[32:35]
	ds_read_b128 v[180:183], v66 offset:34816
	ds_read_b128 v[184:187], v66 offset:39168
	s_waitcnt vmcnt(0) lgkmcnt(1)
	v_mfma_f32_16x16x32_bf16 v[28:31], v[180:183], v[176:179], v[28:31]
	global_load_dwordx4 v[180:183], v[100:101], off
	v_lshl_add_u64 v[100:101], v[100:101], 0, 64
	s_waitcnt lgkmcnt(0)
	v_mfma_f32_16x16x32_bf16 v[24:27], v[184:187], v[176:179], v[24:27]
	ds_read_b128 v[184:187], v66 offset:43520
	ds_read_b128 v[194:197], v66 offset:52224
	s_waitcnt lgkmcnt(1)
	v_mfma_f32_16x16x32_bf16 v[20:23], v[184:187], v[176:179], v[20:23]
	ds_read_b128 v[184:187], v87
	ds_read_b128 v[198:201], v89
	s_waitcnt lgkmcnt(1)
	v_mfma_f32_16x16x32_bf16 v[16:19], v[184:187], v[176:179], v[16:19]
	ds_read_b128 v[176:179], v66 offset:56576
	ds_read_b128 v[184:187], v66 offset:60928
	s_waitcnt vmcnt(0)
	v_mfma_f32_16x16x32_bf16 v[12:15], v[194:197], v[180:183], v[12:15]
	s_waitcnt lgkmcnt(1)
	v_mfma_f32_16x16x32_bf16 v[8:11], v[176:179], v[180:183], v[8:11]
	s_waitcnt lgkmcnt(0)
	v_mfma_f32_16x16x32_bf16 v[4:7], v[184:187], v[180:183], v[4:7]
	v_mfma_f32_16x16x32_bf16 v[0:3], v[198:201], v[180:183], v[0:3]
	s_cbranch_scc1 .LBB0_388
	v_add_u32_e32 v94, s3, v69
	v_mov_b32_e32 v95, v67
	s_lshl_b32 s6, s2, 9
	v_lshlrev_b64 v[94:95], 11, v[94:95]
	s_and_b32 s30, s6, 0x600
	v_lshl_add_u64 v[94:95], s[36:37], 0, v[94:95]
	v_readlane_b32 s8, v254, 23
	v_add_u32_e32 v66, s30, v69
	v_lshl_add_u64 v[94:95], v[94:95], 0, s[30:31]
	v_lshlrev_b32_e32 v96, 1, v68
	v_mov_b32_e32 v97, v67
	v_readlane_b32 s14, v254, 29
	v_readlane_b32 s15, v254, 30
	v_lshl_add_u64 v[94:95], v[94:95], 0, v[96:97]
	v_readlane_b32 s10, v254, 25
	v_lshl_add_u64 v[96:97], v[66:67], 2, s[14:15]
	global_load_dword v230, v[96:97], off
	global_load_dwordx2 v[198:199], v[94:95], off
	global_load_dword v232, v[96:97], off
	global_load_dwordx2 v[200:201], v[94:95], off offset:32
	global_load_dword v234, v[96:97], off
	global_load_dwordx2 v[202:203], v[94:95], off offset:64
	global_load_dword v236, v[96:97], off
	global_load_dwordx2 v[204:205], v[94:95], off offset:96
	global_load_dword v238, v[96:97], off offset:512
	global_load_dwordx2 v[206:207], v[94:95], off offset:128
	global_load_dword v240, v[96:97], off offset:512
	global_load_dwordx2 v[208:209], v[94:95], off offset:160
	global_load_dword v242, v[96:97], off offset:512
	global_load_dwordx2 v[210:211], v[94:95], off offset:192
	global_load_dword v244, v[96:97], off offset:512
	global_load_dwordx2 v[212:213], v[94:95], off offset:224
	global_load_dword v246, v[96:97], off offset:1024
	global_load_dwordx2 v[214:215], v[94:95], off offset:256
	global_load_dword v248, v[96:97], off offset:1024
	global_load_dwordx2 v[216:217], v[94:95], off offset:288
	global_load_dword v250, v[96:97], off offset:1024
	global_load_dwordx2 v[218:219], v[94:95], off offset:320
	global_load_dword v252, v[96:97], off offset:1024
	global_load_dwordx2 v[220:221], v[94:95], off offset:352
	global_load_dword v176, v[96:97], off offset:1536
	global_load_dwordx2 v[222:223], v[94:95], off offset:384
	global_load_dword v178, v[96:97], off offset:1536
	global_load_dwordx2 v[224:225], v[94:95], off offset:416
	global_load_dword v180, v[96:97], off offset:1536
	global_load_dwordx2 v[226:227], v[94:95], off offset:448
	global_load_dword v182, v[96:97], off offset:1536
	global_load_dwordx2 v[228:229], v[94:95], off offset:480
	v_readlane_b32 s11, v254, 26
	v_readlane_b32 s12, v254, 27
	v_readlane_b32 s13, v254, 28
	s_mov_b32 s10, 0x42080000
	s_mov_b32 s12, 0x42000000
	s_mov_b64 s[6:7], 0
	s_mov_b32 s11, 0x420c0000
	s_mov_b32 s13, 0x42040000
	v_readlane_b32 s9, v254, 24
	v_readlane_b32 s16, v254, 31
	v_readlane_b32 s17, v254, 32
	v_readlane_b32 s18, v254, 33
	v_readlane_b32 s19, v254, 34
	v_readlane_b32 s20, v254, 35
	v_readlane_b32 s21, v254, 36
	v_readlane_b32 s22, v254, 37
	v_readlane_b32 s23, v254, 38
	s_waitcnt vmcnt(30)
	v_pk_add_f32 v[60:61], v[60:61], v[230:231] op_sel_hi:[1,0]
	s_waitcnt vmcnt(30)
	v_lshlrev_b32_e32 v100, 16, v198
	v_and_b32_e32 v101, 0xffff0000, v198
	v_lshlrev_b32_e32 v98, 16, v199
	v_and_b32_e32 v99, 0xffff0000, v199
	v_pk_add_f32 v[62:63], v[62:63], v[230:231] op_sel_hi:[1,0]
	v_pk_mul_f32 v[60:61], v[60:61], v[100:101]
	v_pk_mul_f32 v[62:63], v[62:63], v[98:99]
	v_cvt_pk_bf16_f32 v60, v60, v61
	v_cvt_pk_bf16_f32 v61, v62, v63
	global_store_dwordx2 v[94:95], v[60:61], off
	s_waitcnt vmcnt(29)
; __device__ __forceinline__ unsigned pk2(float lo, float hi) { typedef float f2_t __attribute__((ext_vector_type(2))); typedef __bf16 b2_t __attribute__((ext_vector_type(2))); const f2_t v = {lo, hi}; return __builtin_bit_cast(unsigned, __builtin_convertvector(v, b2_t)); }
; __device__ __forceinline__ void sgu_unit(LAS unsigned char* lds, const bf16* U, bf16* Uout, const bf16* Zb, const float* stats, const float* lng, const float* lnb, const bf16* wsm, const float* bs,
;                                          int unit, int tid, int wave, int lane) {
;     ...
;     for (int ct = 0; ct < 16; ++ct) {
;         const float bias = bs[(gq * 4 + (ct >> 2)) * 128 + t];
;         const v2u uw = *(const v2u*)(urow + ct * 16);
;         const float u0 = __uint_as_float(uw.x << 16), u1 = __uint_as_float(uw.x & 0xffff0000u), u2 = __uint_as_float(uw.y << 16), u3 = __uint_as_float(uw.y & 0xffff0000u);
;         v2u w; w.x = pk2(u0 * (acc[ct][0] + bias), u1 * (acc[ct][1] + bias)); w.y = pk2(u2 * (acc[ct][2] + bias), u3 * (acc[ct][3] + bias));
;         *(v2u*)(uorow + ct * 16) = w;
	v_pk_add_f32 v[56:57], v[56:57], v[232:233] op_sel_hi:[1,0]
	s_waitcnt vmcnt(29)
	v_lshlrev_b32_e32 v98, 16, v200
	v_and_b32_e32 v99, 0xffff0000, v200
	v_lshlrev_b32_e32 v62, 16, v201
	v_and_b32_e32 v63, 0xffff0000, v201
	v_pk_add_f32 v[58:59], v[58:59], v[232:233] op_sel_hi:[1,0]
	v_pk_mul_f32 v[56:57], v[56:57], v[98:99]
	v_pk_mul_f32 v[58:59], v[58:59], v[62:63]
	v_cvt_pk_bf16_f32 v56, v56, v57
	v_cvt_pk_bf16_f32 v57, v58, v59
	global_store_dwordx2 v[94:95], v[56:57], off offset:32
	s_waitcnt vmcnt(28)
	v_pk_add_f32 v[52:53], v[52:53], v[234:235] op_sel_hi:[1,0]
	s_waitcnt vmcnt(28)
	v_lshlrev_b32_e32 v60, 16, v202
	v_and_b32_e32 v61, 0xffff0000, v202
	v_lshlrev_b32_e32 v58, 16, v203
	v_and_b32_e32 v59, 0xffff0000, v203
	v_pk_add_f32 v[54:55], v[54:55], v[234:235] op_sel_hi:[1,0]
	v_pk_mul_f32 v[52:53], v[52:53], v[60:61]
	v_pk_mul_f32 v[54:55], v[54:55], v[58:59]
	v_cvt_pk_bf16_f32 v52, v52, v53
	v_cvt_pk_bf16_f32 v53, v54, v55
	global_store_dwordx2 v[94:95], v[52:53], off offset:64
	s_waitcnt vmcnt(27)
	v_pk_add_f32 v[48:49], v[48:49], v[236:237] op_sel_hi:[1,0]
	s_waitcnt vmcnt(27)
	v_lshlrev_b32_e32 v56, 16, v204
	v_and_b32_e32 v57, 0xffff0000, v204
	v_lshlrev_b32_e32 v54, 16, v205
	v_and_b32_e32 v55, 0xffff0000, v205
	v_pk_add_f32 v[50:51], v[50:51], v[236:237] op_sel_hi:[1,0]
	v_pk_mul_f32 v[48:49], v[48:49], v[56:57]
	v_pk_mul_f32 v[50:51], v[50:51], v[54:55]
	v_cvt_pk_bf16_f32 v48, v48, v49
	v_cvt_pk_bf16_f32 v49, v50, v51
	global_store_dwordx2 v[94:95], v[48:49], off offset:96
	s_waitcnt vmcnt(26)
	v_pk_add_f32 v[44:45], v[44:45], v[238:239] op_sel_hi:[1,0]
	s_waitcnt vmcnt(26)
	v_lshlrev_b32_e32 v52, 16, v206
	v_and_b32_e32 v53, 0xffff0000, v206
	v_lshlrev_b32_e32 v50, 16, v207
	v_and_b32_e32 v51, 0xffff0000, v207
	v_pk_add_f32 v[46:47], v[46:47], v[238:239] op_sel_hi:[1,0]
	v_pk_mul_f32 v[44:45], v[44:45], v[52:53]
	v_pk_mul_f32 v[46:47], v[46:47], v[50:51]
	v_cvt_pk_bf16_f32 v44, v44, v45
	v_cvt_pk_bf16_f32 v45, v46, v47
	global_store_dwordx2 v[94:95], v[44:45], off offset:128
	s_waitcnt vmcnt(25)
	v_pk_add_f32 v[40:41], v[40:41], v[240:241] op_sel_hi:[1,0]
	s_waitcnt vmcnt(25)
	v_lshlrev_b32_e32 v48, 16, v208
	v_and_b32_e32 v49, 0xffff0000, v208
	v_lshlrev_b32_e32 v46, 16, v209
	v_and_b32_e32 v47, 0xffff0000, v209
	v_pk_add_f32 v[42:43], v[42:43], v[240:241] op_sel_hi:[1,0]
	v_pk_mul_f32 v[40:41], v[40:41], v[48:49]
	v_pk_mul_f32 v[42:43], v[42:43], v[46:47]
	v_cvt_pk_bf16_f32 v40, v40, v41
	v_cvt_pk_bf16_f32 v41, v42, v43
	global_store_dwordx2 v[94:95], v[40:41], off offset:160
	s_waitcnt vmcnt(24)
	v_pk_add_f32 v[36:37], v[36:37], v[242:243] op_sel_hi:[1,0]
	s_waitcnt vmcnt(24)
	v_lshlrev_b32_e32 v44, 16, v210
	v_and_b32_e32 v45, 0xffff0000, v210
	v_lshlrev_b32_e32 v42, 16, v211
	v_and_b32_e32 v43, 0xffff0000, v211
	v_pk_add_f32 v[38:39], v[38:39], v[242:243] op_sel_hi:[1,0]
	v_pk_mul_f32 v[36:37], v[36:37], v[44:45]
	v_pk_mul_f32 v[38:39], v[38:39], v[42:43]
	v_cvt_pk_bf16_f32 v36, v36, v37
	v_cvt_pk_bf16_f32 v37, v38, v39
	global_store_dwordx2 v[94:95], v[36:37], off offset:192
	s_waitcnt vmcnt(23)
	v_pk_add_f32 v[32:33], v[32:33], v[244:245] op_sel_hi:[1,0]
	s_waitcnt vmcnt(23)
	v_lshlrev_b32_e32 v40, 16, v212
	v_and_b32_e32 v41, 0xffff0000, v212
	v_lshlrev_b32_e32 v38, 16, v213
	v_and_b32_e32 v39, 0xffff0000, v213
	v_pk_add_f32 v[34:35], v[34:35], v[244:245] op_sel_hi:[1,0]
	v_pk_mul_f32 v[32:33], v[32:33], v[40:41]
	v_pk_mul_f32 v[34:35], v[34:35], v[38:39]
	v_cvt_pk_bf16_f32 v32, v32, v33
	v_cvt_pk_bf16_f32 v33, v34, v35
	global_store_dwordx2 v[94:95], v[32:33], off offset:224
	s_waitcnt vmcnt(22)
	v_pk_add_f32 v[28:29], v[28:29], v[246:247] op_sel_hi:[1,0]
	s_waitcnt vmcnt(22)
; __device__ __forceinline__ unsigned pk2(float lo, float hi) { typedef float f2_t __attribute__((ext_vector_type(2))); typedef __bf16 b2_t __attribute__((ext_vector_type(2))); const f2_t v = {lo, hi}; return __builtin_bit_cast(unsigned, __builtin_convertvector(v, b2_t)); }
; __device__ __forceinline__ void sgu_unit(LAS unsigned char* lds, const bf16* U, bf16* Uout, const bf16* Zb, const float* stats, const float* lng, const float* lnb, const bf16* wsm, const float* bs,
;                                          int unit, int tid, int wave, int lane) {
;     ...
;     for (int ct = 0; ct < 16; ++ct) {
;         const float bias = bs[(gq * 4 + (ct >> 2)) * 128 + t];
;         const v2u uw = *(const v2u*)(urow + ct * 16);
;         const float u0 = __uint_as_float(uw.x << 16), u1 = __uint_as_float(uw.x & 0xffff0000u), u2 = __uint_as_float(uw.y << 16), u3 = __uint_as_float(uw.y & 0xffff0000u);
;         v2u w; w.x = pk2(u0 * (acc[ct][0] + bias), u1 * (acc[ct][1] + bias)); w.y = pk2(u2 * (acc[ct][2] + bias), u3 * (acc[ct][3] + bias));
;         *(v2u*)(uorow + ct * 16) = w;
	v_lshlrev_b32_e32 v36, 16, v214
	v_and_b32_e32 v37, 0xffff0000, v214
	v_lshlrev_b32_e32 v34, 16, v215
	v_and_b32_e32 v35, 0xffff0000, v215
	v_pk_add_f32 v[30:31], v[30:31], v[246:247] op_sel_hi:[1,0]
	v_pk_mul_f32 v[28:29], v[28:29], v[36:37]
	v_pk_mul_f32 v[30:31], v[30:31], v[34:35]
	v_cvt_pk_bf16_f32 v28, v28, v29
	v_cvt_pk_bf16_f32 v29, v30, v31
	global_store_dwordx2 v[94:95], v[28:29], off offset:256
	s_waitcnt vmcnt(21)
	v_pk_add_f32 v[24:25], v[24:25], v[248:249] op_sel_hi:[1,0]
	s_waitcnt vmcnt(21)
	v_lshlrev_b32_e32 v32, 16, v216
	v_and_b32_e32 v33, 0xffff0000, v216
	v_lshlrev_b32_e32 v30, 16, v217
	v_and_b32_e32 v31, 0xffff0000, v217
	v_pk_add_f32 v[26:27], v[26:27], v[248:249] op_sel_hi:[1,0]
	v_pk_mul_f32 v[24:25], v[24:25], v[32:33]
	v_pk_mul_f32 v[26:27], v[26:27], v[30:31]
	v_cvt_pk_bf16_f32 v24, v24, v25
	v_cvt_pk_bf16_f32 v25, v26, v27
	global_store_dwordx2 v[94:95], v[24:25], off offset:288
	s_waitcnt vmcnt(20)
	v_pk_add_f32 v[20:21], v[20:21], v[250:251] op_sel_hi:[1,0]
	s_waitcnt vmcnt(20)
	v_lshlrev_b32_e32 v28, 16, v218
	v_and_b32_e32 v29, 0xffff0000, v218
	v_lshlrev_b32_e32 v26, 16, v219
	v_and_b32_e32 v27, 0xffff0000, v219
	v_pk_add_f32 v[22:23], v[22:23], v[250:251] op_sel_hi:[1,0]
	v_pk_mul_f32 v[20:21], v[20:21], v[28:29]
	v_pk_mul_f32 v[22:23], v[22:23], v[26:27]
	v_cvt_pk_bf16_f32 v20, v20, v21
	v_cvt_pk_bf16_f32 v21, v22, v23
	global_store_dwordx2 v[94:95], v[20:21], off offset:320
	s_waitcnt vmcnt(19)
	v_pk_add_f32 v[16:17], v[16:17], v[252:253] op_sel_hi:[1,0]
	s_waitcnt vmcnt(19)
	v_lshlrev_b32_e32 v24, 16, v220
	v_and_b32_e32 v25, 0xffff0000, v220
	v_lshlrev_b32_e32 v22, 16, v221
	v_and_b32_e32 v23, 0xffff0000, v221
	v_pk_add_f32 v[18:19], v[18:19], v[252:253] op_sel_hi:[1,0]
	v_pk_mul_f32 v[16:17], v[16:17], v[24:25]
	v_pk_mul_f32 v[18:19], v[18:19], v[22:23]
	v_cvt_pk_bf16_f32 v16, v16, v17
	v_cvt_pk_bf16_f32 v17, v18, v19
	global_store_dwordx2 v[94:95], v[16:17], off offset:352
	s_waitcnt vmcnt(18)
	v_pk_add_f32 v[12:13], v[12:13], v[176:177] op_sel_hi:[1,0]
	s_waitcnt vmcnt(18)
	v_lshlrev_b32_e32 v20, 16, v222
	v_and_b32_e32 v21, 0xffff0000, v222
	v_lshlrev_b32_e32 v18, 16, v223
	v_and_b32_e32 v19, 0xffff0000, v223
	v_pk_add_f32 v[14:15], v[14:15], v[176:177] op_sel_hi:[1,0]
	v_pk_mul_f32 v[12:13], v[12:13], v[20:21]
	v_pk_mul_f32 v[14:15], v[14:15], v[18:19]
	v_cvt_pk_bf16_f32 v12, v12, v13
	v_cvt_pk_bf16_f32 v13, v14, v15
	global_store_dwordx2 v[94:95], v[12:13], off offset:384
	s_waitcnt vmcnt(17)
	v_pk_add_f32 v[8:9], v[8:9], v[178:179] op_sel_hi:[1,0]
	s_waitcnt vmcnt(17)
	v_lshlrev_b32_e32 v16, 16, v224
	v_and_b32_e32 v17, 0xffff0000, v224
	v_lshlrev_b32_e32 v14, 16, v225
	v_and_b32_e32 v15, 0xffff0000, v225
	v_pk_add_f32 v[10:11], v[10:11], v[178:179] op_sel_hi:[1,0]
	v_pk_mul_f32 v[8:9], v[8:9], v[16:17]
	v_pk_mul_f32 v[10:11], v[10:11], v[14:15]
	v_cvt_pk_bf16_f32 v8, v8, v9
	v_cvt_pk_bf16_f32 v9, v10, v11
	global_store_dwordx2 v[94:95], v[8:9], off offset:416
	s_waitcnt vmcnt(16)
	v_pk_add_f32 v[4:5], v[4:5], v[180:181] op_sel_hi:[1,0]
	s_waitcnt vmcnt(16)
	v_lshlrev_b32_e32 v12, 16, v226
	v_and_b32_e32 v13, 0xffff0000, v226
	v_lshlrev_b32_e32 v10, 16, v227
	v_and_b32_e32 v11, 0xffff0000, v227
	v_pk_add_f32 v[6:7], v[6:7], v[180:181] op_sel_hi:[1,0]
	v_pk_mul_f32 v[4:5], v[4:5], v[12:13]
	v_pk_mul_f32 v[6:7], v[6:7], v[10:11]
	v_cvt_pk_bf16_f32 v4, v4, v5
	v_cvt_pk_bf16_f32 v5, v6, v7
	global_store_dwordx2 v[94:95], v[4:5], off offset:448
	s_waitcnt vmcnt(15)
	v_pk_add_f32 v[0:1], v[0:1], v[182:183] op_sel_hi:[1,0]
	s_waitcnt vmcnt(15)
	v_lshlrev_b32_e32 v8, 16, v228
	v_and_b32_e32 v9, 0xffff0000, v228
	v_lshlrev_b32_e32 v6, 16, v229
	v_and_b32_e32 v7, 0xffff0000, v229
	v_pk_add_f32 v[2:3], v[2:3], v[182:183] op_sel_hi:[1,0]
	v_pk_mul_f32 v[0:1], v[0:1], v[8:9]
	v_pk_mul_f32 v[2:3], v[2:3], v[6:7]
	v_cvt_pk_bf16_f32 v0, v0, v1
	v_cvt_pk_bf16_f32 v1, v2, v3
	global_store_dwordx2 v[94:95], v[0:1], off offset:480
